# v32 plus: GU-to-D hand-off, the polling wave's L1 invalidate issued before the first poll (overlaps the poll round trip) at the two prologue hand-off sites
# speedup vs baseline: 1.0037x; 1.0037x over previous
; __device__ __forceinline__ void wait_panel(const unsigned* ready, int pm, unsigned need, unsigned* tmo, int wave) {
;     if (wave == 0) {
;         const unsigned long long t0 = __builtin_amdgcn_s_memrealtime(); unsigned polls = 0;
;         while ((unsigned)__builtin_amdgcn_readfirstlane(__hip_atomic_load(ready + 64 * pm, __ATOMIC_RELAXED, __HIP_MEMORY_SCOPE_AGENT)) < need) {
; __global__ void __launch_bounds__(NTHR, 2) fwd_kernel(Args a_unused) {
;     ...
;                 { EpiGU E{(bf16*)(ws + WS_HID)}; pg8::Gemm g_{(const pg8::bf16_t*)(ws + WS_H), (const pg8::bf16_t*)(ws + WS_WGU + (size_t)(l * 2 + s) * 10752 * 2048 * 2), 2048, 2048, 2048};
;                   pg8::GuOrder S_; S_.init(F.G, F.bx, pan); pg8::gemm_phase<EpiGU, pg8::GuOrder, true, true>(F.lds, g_, S_, E, F.tid); }
;                 { const float* modp = MODL + (s == 0 ? 2 : 8) * D; const unsigned char* wd = ws + WS_WD + (size_t)(l * 2 + s) * 2048 * 5376 * 2;
;                   { EpiRes E{(h16*)(ws + WS_X), modp, 0.5f}; pg8::Gemm g_{(const pg8::bf16_t*)(ws + WS_HID), (const pg8::bf16_t*)wd, 5376, 5376, 5376};
;                     pg8::DOrder S_; S_.init(F.G, F.bx, F.wave, pan, 42u * 8u, tmo); pg8::gemm_phase<EpiRes, pg8::DOrder, true, true>(F.lds, g_, S_, E, F.tid); }
.LBB0_2340:
	v_readlane_b32 s20, v246, 17
	v_readlane_b32 s21, v246, 18
	s_lshl_b64 s[20:21], s[20:21], 2
	s_add_u32 s6, s26, s20
	s_addc_u32 s17, s27, s21
	v_readlane_b32 s20, v246, 30
	v_readlane_b32 s21, v246, 31
	s_and_b64 s[20:21], s[20:21], exec
	s_movk_i32 s19, 0x4000
	s_cselect_b32 s19, s19, 0x10000
	s_add_u32 s6, s6, s19
	s_addc_u32 s17, s17, 0
	s_add_u32 s54, s6, 0x3c400000
	s_addc_u32 s55, s17, 0
	s_mul_hi_u32 s6, s18, 0x1500000
	s_mul_i32 s18, s18, 0x1500000
	s_add_u32 s17, s26, s18
	s_addc_u32 s6, s27, s6
	s_add_u32 s18, s17, 0x15100000
	s_addc_u32 s19, s6, 0
	s_add_u32 s56, s26, 0x8000
	s_addc_u32 s57, s27, 0
	s_andn2_b64 vcc, exec, s[22:23]
	s_cbranch_vccnz .LBB0_2393
	s_and_b64 vcc, exec, s[4:5]
	s_cbranch_vccnz .LBB0_2356
	s_memrealtime s[22:23]
	buffer_inv sc1
	s_lshl_b32 s20, s12, 6
	s_ashr_i32 s21, s20, 31
	s_lshl_b64 s[20:21], s[20:21], 2
	s_add_u32 s36, s38, s20
	s_addc_u32 s37, s30, s21
	s_mov_b32 s6, 1
	s_branch .LBB0_2345

; __device__ __forceinline__ void wait_panel(const unsigned* ready, int pm, unsigned need, unsigned* tmo, int wave) {
;     ...
;         __builtin_amdgcn_fence(__ATOMIC_ACQUIRE, "agent");
;         asm volatile("s_waitcnt vmcnt(0)" ::: "memory");
.LBB0_2355:
	s_waitcnt vmcnt(0) lgkmcnt(0)
	s_waitcnt vmcnt(0)

; __device__ __forceinline__ void wait_panel(const unsigned* ready, int pm, unsigned need, unsigned* tmo, int wave) {
;     if (wave == 0) {
;         const unsigned long long t0 = __builtin_amdgcn_s_memrealtime(); unsigned polls = 0;
;         while ((unsigned)__builtin_amdgcn_readfirstlane(__hip_atomic_load(ready + 64 * pm, __ATOMIC_RELAXED, __HIP_MEMORY_SCOPE_AGENT)) < need) {
; __global__ void __launch_bounds__(NTHR, 2) fwd_kernel(Args a_unused) {
;     ...
;                     pg8::SplitKCounted S_; S_.init(32, 8, 7, 768, F.G, (F.G != 256) ? F.bx : (erank >= 0 ? erank : 100000)); S_.wave = F.wave; S_.cnt = pan; S_.need = 42u * 8u; S_.tmo = tmo;
.LBB0_2397:
	s_and_b64 vcc, exec, s[4:5]
	s_cbranch_vccnz .LBB0_2412
	s_memrealtime s[22:23]
	buffer_inv sc1
	s_add_u32 s40, s38, 0x2000
	s_addc_u32 s41, s30, 0
	s_mov_b32 s11, 1
	s_branch .LBB0_2401
